# dilated window masks: one-sided compares per boundary tile (inline constants, 3 rotating mask registers, no per-element add or nop)
# speedup vs baseline: 1.0065x; 1.0021x over previous
.LBB0_1397:
	s_cmp_lt_i32 s0, s42
	s_cselect_b64 s[4:5], -1, 0
	s_cmp_gt_i32 s0, s43
	s_cselect_b64 s[0:1], -1, 0
	s_or_b64 s[0:1], s[4:5], s[0:1]
	s_and_b64 vcc, exec, s[0:1]
	s_cbranch_vccnz .LBB0_1404
	s_lshl_b32 s0, s46, 13
	v_add_u32_e32 v34, s0, v99
	v_add_u32_e32 v137, s0, v105
	ds_read_b128 v[140:143], v34
	ds_read_b128 v[144:147], v34 offset:512
	ds_read_b128 v[148:151], v34 offset:2048
	ds_read_b128 v[152:155], v34 offset:2560
	ds_read_b128 v[156:159], v34 offset:4096
	ds_read_b128 v[160:163], v34 offset:4608
	ds_read_b128 v[164:167], v34 offset:6144
	ds_read_b128 v[168:171], v34 offset:6656
	ds_read_b64_tr_b16 v[94:95], v137 offset:32768
	ds_read_b64_tr_b16 v[96:97], v137 offset:33280
	ds_read_b64_tr_b16 v[90:91], v137 offset:33792
	ds_read_b64_tr_b16 v[92:93], v137 offset:34304
	ds_read_b64_tr_b16 v[86:87], v137 offset:34816
	ds_read_b64_tr_b16 v[88:89], v137 offset:35328
	ds_read_b64_tr_b16 v[82:83], v137 offset:35840
	ds_read_b64_tr_b16 v[84:85], v137 offset:36352
	v_sub_f32_e32 v34, 0, v133
	v_cmp_eq_f32_e64 s[4:5], s30, v133
	s_nop 1
	v_cndmask_b32_e64 v34, v34, 0, s[4:5]
	v_mov_b32_e32 v35, v34
	v_mov_b32_e32 v36, v34
	v_mov_b32_e32 v37, v34
	v_mov_b32_e32 v38, v34
	v_mov_b32_e32 v39, v34
	v_mov_b32_e32 v40, v34
	v_mov_b32_e32 v41, v34
	v_mov_b32_e32 v42, v34
	v_mov_b32_e32 v43, v34
	v_mov_b32_e32 v44, v34
	v_mov_b32_e32 v45, v34
	v_mov_b32_e32 v46, v34
	v_mov_b32_e32 v47, v34
	v_mov_b32_e32 v48, v34
	v_mov_b32_e32 v49, v34
	s_waitcnt lgkmcnt(14)
	s_nop 0
	v_mfma_f32_32x32x16_bf16 v[50:65], v[140:143], v[78:81], v[34:49]
	v_mfma_f32_32x32x16_bf16 v[34:49], v[144:147], v[78:81], v[34:49]
	s_waitcnt lgkmcnt(13)
	v_mfma_f32_32x32x16_bf16 v[50:65], v[148:151], v[74:77], v[50:65]
	s_waitcnt lgkmcnt(12)
	v_mfma_f32_32x32x16_bf16 v[34:49], v[152:155], v[74:77], v[34:49]
	s_waitcnt lgkmcnt(11)
	v_mfma_f32_32x32x16_bf16 v[50:65], v[156:159], v[70:73], v[50:65]
	s_waitcnt lgkmcnt(10)
	v_mfma_f32_32x32x16_bf16 v[34:49], v[160:163], v[70:73], v[34:49]
	s_waitcnt lgkmcnt(9)
	v_mfma_f32_32x32x16_bf16 v[50:65], v[164:167], v[66:69], v[50:65]
	s_waitcnt lgkmcnt(8)
	v_mfma_f32_32x32x16_bf16 v[34:49], v[168:171], v[66:69], v[34:49]
	s_cmp_eq_u32 s45, s47
	s_cbranch_scc1 .LBB0_1400
	s_cmp_lt_i32 s47, s45
	s_cbranch_scc1 .Ldil_mask_lo
	v_cmp_le_i32_e32 vcc, 0, v135
	v_cmp_le_i32_e64 s[88:89], 32, v135
	v_cmp_le_i32_e64 s[90:91], 1, v135
	s_nop 7
	s_nop 1
	v_cndmask_b32_e32 v50, v130, v50, vcc
	v_cmp_le_i32_e32 vcc, 33, v135
	v_cndmask_b32_e64 v34, v130, v34, s[88:89]
	v_cmp_le_i32_e64 s[88:89], 2, v135
	v_cndmask_b32_e64 v51, v130, v51, s[90:91]
	v_cmp_le_i32_e64 s[90:91], 34, v135
	v_cndmask_b32_e32 v35, v130, v35, vcc
	v_cmp_le_i32_e32 vcc, 3, v135
	v_cndmask_b32_e64 v52, v130, v52, s[88:89]
	v_cmp_le_i32_e64 s[88:89], 35, v135
	v_cndmask_b32_e64 v36, v130, v36, s[90:91]
	v_cmp_le_i32_e64 s[90:91], 8, v135
	v_cndmask_b32_e32 v53, v130, v53, vcc
	v_cmp_le_i32_e32 vcc, 40, v135
	v_cndmask_b32_e64 v37, v130, v37, s[88:89]
	v_cmp_le_i32_e64 s[88:89], 9, v135
	v_cndmask_b32_e64 v54, v130, v54, s[90:91]
	v_cmp_le_i32_e64 s[90:91], 41, v135
	v_cndmask_b32_e32 v38, v130, v38, vcc
	v_cmp_le_i32_e32 vcc, 10, v135
	v_cndmask_b32_e64 v55, v130, v55, s[88:89]
	v_cmp_le_i32_e64 s[88:89], 42, v135
	v_cndmask_b32_e64 v39, v130, v39, s[90:91]
	v_cmp_le_i32_e64 s[90:91], 11, v135
	v_cndmask_b32_e32 v56, v130, v56, vcc
	v_cmp_le_i32_e32 vcc, 43, v135
	v_cndmask_b32_e64 v40, v130, v40, s[88:89]
	v_cmp_le_i32_e64 s[88:89], 16, v135
	v_cndmask_b32_e64 v57, v130, v57, s[90:91]
	v_cmp_le_i32_e64 s[90:91], 48, v135
	v_cndmask_b32_e32 v41, v130, v41, vcc
	v_cmp_le_i32_e32 vcc, 17, v135
	v_cndmask_b32_e64 v58, v130, v58, s[88:89]
	v_cmp_le_i32_e64 s[88:89], 49, v135
	v_cndmask_b32_e64 v42, v130, v42, s[90:91]
	v_cmp_le_i32_e64 s[90:91], 18, v135
	v_cndmask_b32_e32 v59, v130, v59, vcc
	v_cmp_le_i32_e32 vcc, 50, v135
	v_cndmask_b32_e64 v43, v130, v43, s[88:89]
	v_cmp_le_i32_e64 s[88:89], 19, v135
	v_cndmask_b32_e64 v60, v130, v60, s[90:91]
	v_cmp_le_i32_e64 s[90:91], 51, v135
	v_cndmask_b32_e32 v44, v130, v44, vcc
	v_cmp_le_i32_e32 vcc, 24, v135
	v_cndmask_b32_e64 v61, v130, v61, s[88:89]
	v_cmp_le_i32_e64 s[88:89], 56, v135
	v_cndmask_b32_e64 v45, v130, v45, s[90:91]
	v_cmp_le_i32_e64 s[90:91], 25, v135
	v_cndmask_b32_e32 v62, v130, v62, vcc
	v_cmp_le_i32_e32 vcc, 57, v135
	v_cndmask_b32_e64 v46, v130, v46, s[88:89]
	v_cmp_le_i32_e64 s[88:89], 26, v135
	v_cndmask_b32_e64 v63, v130, v63, s[90:91]
	v_cmp_le_i32_e64 s[90:91], 58, v135
	v_cndmask_b32_e32 v47, v130, v47, vcc
	v_cmp_le_i32_e32 vcc, 27, v135
	v_cndmask_b32_e64 v64, v130, v64, s[88:89]
	v_cmp_le_i32_e64 s[88:89], 59, v135
	v_cndmask_b32_e64 v48, v130, v48, s[90:91]
	v_cndmask_b32_e32 v65, v130, v65, vcc
	v_cndmask_b32_e64 v49, v130, v49, s[88:89]
	s_branch .LBB0_1400
.Ldil_mask_lo:
	v_add_u32_e32 v139, 0xffffff80, v135
	v_cmp_ge_i32_e32 vcc, 0, v139
	v_cmp_ge_i32_e64 s[88:89], 32, v139
	v_cmp_ge_i32_e64 s[90:91], 1, v139
	s_nop 7
	s_nop 1
	v_cndmask_b32_e32 v50, v130, v50, vcc
	v_cmp_ge_i32_e32 vcc, 33, v139
	v_cndmask_b32_e64 v34, v130, v34, s[88:89]
	v_cmp_ge_i32_e64 s[88:89], 2, v139
	v_cndmask_b32_e64 v51, v130, v51, s[90:91]
	v_cmp_ge_i32_e64 s[90:91], 34, v139
	v_cndmask_b32_e32 v35, v130, v35, vcc
	v_cmp_ge_i32_e32 vcc, 3, v139
	v_cndmask_b32_e64 v52, v130, v52, s[88:89]
	v_cmp_ge_i32_e64 s[88:89], 35, v139
	v_cndmask_b32_e64 v36, v130, v36, s[90:91]
	v_cmp_ge_i32_e64 s[90:91], 8, v139
	v_cndmask_b32_e32 v53, v130, v53, vcc
	v_cmp_ge_i32_e32 vcc, 40, v139
	v_cndmask_b32_e64 v37, v130, v37, s[88:89]
	v_cmp_ge_i32_e64 s[88:89], 9, v139
	v_cndmask_b32_e64 v54, v130, v54, s[90:91]
	v_cmp_ge_i32_e64 s[90:91], 41, v139
	v_cndmask_b32_e32 v38, v130, v38, vcc
	v_cmp_ge_i32_e32 vcc, 10, v139
	v_cndmask_b32_e64 v55, v130, v55, s[88:89]
	v_cmp_ge_i32_e64 s[88:89], 42, v139
	v_cndmask_b32_e64 v39, v130, v39, s[90:91]
	v_cmp_ge_i32_e64 s[90:91], 11, v139
	v_cndmask_b32_e32 v56, v130, v56, vcc
	v_cmp_ge_i32_e32 vcc, 43, v139
	v_cndmask_b32_e64 v40, v130, v40, s[88:89]
	v_cmp_ge_i32_e64 s[88:89], 16, v139
	v_cndmask_b32_e64 v57, v130, v57, s[90:91]
	v_cmp_ge_i32_e64 s[90:91], 48, v139
	v_cndmask_b32_e32 v41, v130, v41, vcc
	v_cmp_ge_i32_e32 vcc, 17, v139
	v_cndmask_b32_e64 v58, v130, v58, s[88:89]
	v_cmp_ge_i32_e64 s[88:89], 49, v139
	v_cndmask_b32_e64 v42, v130, v42, s[90:91]
	v_cmp_ge_i32_e64 s[90:91], 18, v139
	v_cndmask_b32_e32 v59, v130, v59, vcc
	v_cmp_ge_i32_e32 vcc, 50, v139
	v_cndmask_b32_e64 v43, v130, v43, s[88:89]
	v_cmp_ge_i32_e64 s[88:89], 19, v139
	v_cndmask_b32_e64 v60, v130, v60, s[90:91]
	v_cmp_ge_i32_e64 s[90:91], 51, v139
	v_cndmask_b32_e32 v44, v130, v44, vcc
	v_cmp_ge_i32_e32 vcc, 24, v139
	v_cndmask_b32_e64 v61, v130, v61, s[88:89]
	v_cmp_ge_i32_e64 s[88:89], 56, v139
	v_cndmask_b32_e64 v45, v130, v45, s[90:91]
	v_cmp_ge_i32_e64 s[90:91], 25, v139
	v_cndmask_b32_e32 v62, v130, v62, vcc
	v_cmp_ge_i32_e32 vcc, 57, v139
	v_cndmask_b32_e64 v46, v130, v46, s[88:89]
	v_cmp_ge_i32_e64 s[88:89], 26, v139
	v_cndmask_b32_e64 v63, v130, v63, s[90:91]
	v_cmp_ge_i32_e64 s[90:91], 58, v139
	v_cndmask_b32_e32 v47, v130, v47, vcc
	v_cmp_ge_i32_e32 vcc, 27, v139
	v_cndmask_b32_e64 v64, v130, v64, s[88:89]
	v_cmp_ge_i32_e64 s[88:89], 59, v139
	v_cndmask_b32_e64 v48, v130, v48, s[90:91]
	v_cndmask_b32_e32 v65, v130, v65, vcc
	v_cndmask_b32_e64 v49, v130, v49, s[88:89]
